# strategy lever 4: static priority raise for waves 4-7 in the in-proj GEMM K-loop (loop body duplicated per wave half; flips 2/1 instead of 1/0 for the younger half)
# baseline (speedup 1.0000x reference)
.LBB0_132:
	s_ashr_i32 s19, s18, 31
	v_cmp_lt_i64_e32 vcc, s[20:21], v[142:143]
	s_lshl_b64 s[20:21], s[18:19], 19
	s_add_u32 s20, s40, s20
	s_addc_u32 s21, s41, s21
	s_and_b64 s[22:23], vcc, exec
	s_cselect_b32 s15, s21, s25
	s_cselect_b32 s17, s20, s24
	s_ashr_i32 s9, s8, 31
	s_lshl_b64 s[22:23], s[8:9], 19
	s_add_u32 s22, s6, s22
	s_addc_u32 s23, s7, s23
	s_and_b64 s[34:35], vcc, exec
	s_cselect_b32 s9, s23, s53
	s_cselect_b32 s19, s22, s52
	s_add_u32 s24, s24, 0x40080
	s_addc_u32 s25, s25, 0
	s_add_u32 s89, s52, 0x100
	v_mov_b32_e32 v28, 0
	s_addc_u32 s90, s53, 0
	s_mov_b32 s91, -2
	v_mov_b32_e32 v29, v28
	v_mov_b32_e32 v30, v28
	v_mov_b32_e32 v31, v28
	v_mov_b32_e32 v36, v28
	v_mov_b32_e32 v37, v28
	v_mov_b32_e32 v38, v28
	v_mov_b32_e32 v39, v28
	v_mov_b32_e32 v40, v28
	v_mov_b32_e32 v41, v28
	v_mov_b32_e32 v42, v28
	v_mov_b32_e32 v43, v28
	v_mov_b32_e32 v44, v28
	v_mov_b32_e32 v45, v28
	v_mov_b32_e32 v46, v28
	v_mov_b32_e32 v47, v28
	v_mov_b32_e32 v60, v28
	v_mov_b32_e32 v61, v28
	v_mov_b32_e32 v62, v28
	v_mov_b32_e32 v63, v28
	v_mov_b32_e32 v68, v28
	v_mov_b32_e32 v69, v28
	v_mov_b32_e32 v70, v28
	v_mov_b32_e32 v71, v28
	v_mov_b32_e32 v80, v28
	v_mov_b32_e32 v81, v28
	v_mov_b32_e32 v82, v28
	v_mov_b32_e32 v83, v28
	v_mov_b32_e32 v88, v28
	v_mov_b32_e32 v89, v28
	v_mov_b32_e32 v90, v28
	v_mov_b32_e32 v91, v28
	v_mov_b32_e32 v0, v28
	v_mov_b32_e32 v1, v28
	v_mov_b32_e32 v2, v28
	v_mov_b32_e32 v3, v28
	v_mov_b32_e32 v4, v28
	v_mov_b32_e32 v5, v28
	v_mov_b32_e32 v6, v28
	v_mov_b32_e32 v7, v28
	v_mov_b32_e32 v8, v28
	v_mov_b32_e32 v9, v28
	v_mov_b32_e32 v10, v28
	v_mov_b32_e32 v11, v28
	v_mov_b32_e32 v12, v28
	v_mov_b32_e32 v13, v28
	v_mov_b32_e32 v14, v28
	v_mov_b32_e32 v15, v28
	v_mov_b32_e32 v16, v28
	v_mov_b32_e32 v17, v28
	v_mov_b32_e32 v18, v28
	v_mov_b32_e32 v19, v28
	v_mov_b32_e32 v20, v28
	v_mov_b32_e32 v21, v28
	v_mov_b32_e32 v22, v28
	v_mov_b32_e32 v23, v28
	v_mov_b32_e32 v24, v28
	v_mov_b32_e32 v25, v28
	v_mov_b32_e32 v26, v28
	v_mov_b32_e32 v27, v28
	v_mov_b32_e32 v32, v28
	v_mov_b32_e32 v33, v28
	v_mov_b32_e32 v34, v28
	v_mov_b32_e32 v35, v28
	v_mov_b32_e32 v96, v28
	v_mov_b32_e32 v97, v28
	v_mov_b32_e32 v98, v28
	v_mov_b32_e32 v99, v28
	v_mov_b32_e32 v100, v28
	v_mov_b32_e32 v101, v28
	v_mov_b32_e32 v102, v28
	v_mov_b32_e32 v103, v28
	v_mov_b32_e32 v104, v28
	v_mov_b32_e32 v105, v28
	v_mov_b32_e32 v106, v28
	v_mov_b32_e32 v107, v28
	v_mov_b32_e32 v108, v28
	v_mov_b32_e32 v109, v28
	v_mov_b32_e32 v110, v28
	v_mov_b32_e32 v111, v28
	v_mov_b32_e32 v112, v28
	v_mov_b32_e32 v113, v28
	v_mov_b32_e32 v114, v28
	v_mov_b32_e32 v115, v28
	v_mov_b32_e32 v116, v28
	v_mov_b32_e32 v117, v28
	v_mov_b32_e32 v118, v28
	v_mov_b32_e32 v119, v28
	v_mov_b32_e32 v120, v28
	v_mov_b32_e32 v121, v28
	v_mov_b32_e32 v122, v28
	v_mov_b32_e32 v123, v28
	v_mov_b32_e32 v124, v28
	v_mov_b32_e32 v125, v28
	v_mov_b32_e32 v126, v28
	v_mov_b32_e32 v127, v28
	v_mov_b32_e32 v48, v28
	v_mov_b32_e32 v49, v28
	v_mov_b32_e32 v50, v28
	v_mov_b32_e32 v51, v28
	v_mov_b32_e32 v52, v28
	v_mov_b32_e32 v53, v28
	v_mov_b32_e32 v54, v28
	v_mov_b32_e32 v55, v28
	v_mov_b32_e32 v56, v28
	v_mov_b32_e32 v57, v28
	v_mov_b32_e32 v58, v28
	v_mov_b32_e32 v59, v28
	v_mov_b32_e32 v64, v28
	v_mov_b32_e32 v65, v28
	v_mov_b32_e32 v66, v28
	v_mov_b32_e32 v67, v28
	v_mov_b32_e32 v72, v28
	v_mov_b32_e32 v73, v28
	v_mov_b32_e32 v74, v28
	v_mov_b32_e32 v75, v28
	v_mov_b32_e32 v76, v28
	v_mov_b32_e32 v77, v28
	v_mov_b32_e32 v78, v28
	v_mov_b32_e32 v79, v28
	v_mov_b32_e32 v84, v28
	v_mov_b32_e32 v85, v28
	v_mov_b32_e32 v86, v28
	v_mov_b32_e32 v87, v28
	v_mov_b32_e32 v92, v28
	v_mov_b32_e32 v93, v28
	v_mov_b32_e32 v94, v28
	v_mov_b32_e32 v95, v28
	s_cmp_lt_u32 s86, 0x100
	s_cbranch_scc0 .Lgk_b
.LBB0_133:
	ds_read_b128 v[154:157], v151
	ds_read_b128 v[158:161], v151 offset:1024
	ds_read_b128 v[162:165], v151 offset:2048
	ds_read_b128 v[166:169], v151 offset:3072
	s_add_u32 s34, s24, 0xfffc0080
	s_addc_u32 s35, s25, -1
	s_cmp_eq_u32 s91, 12
	s_cselect_b32 s57, s15, s35
	s_cselect_b32 s56, s17, s34
	s_cselect_b32 s53, s9, s90
	s_cselect_b32 s52, s19, s89
	v_lshl_add_u64 v[146:147], s[24:25], 0, v[138:139]
	s_add_i32 m0, s29, 0xc000
	ds_read_b128 v[170:173], v152
	ds_read_b128 v[174:177], v152 offset:1024
	ds_read_b128 v[178:181], v152 offset:2048
	ds_read_b128 v[182:185], v152 offset:3072
	ds_read_b128 v[186:189], v152 offset:4096
	ds_read_b128 v[190:193], v152 offset:5120
	ds_read_b128 v[196:199], v152 offset:6144
	ds_read_b128 v[200:203], v152 offset:7168
	global_load_lds_dwordx4 v[146:147], off
	v_lshl_add_u64 v[146:147], s[24:25], 0, v[140:141]
	s_add_i32 m0, s29, 0xe000
	s_nop 0
	global_load_lds_dwordx4 v[146:147], off
	s_waitcnt lgkmcnt(8)
	s_barrier
	s_waitcnt lgkmcnt(0)
	s_setprio 1
	s_waitcnt lgkmcnt(0)
	v_mfma_f32_16x16x32_bf16 v[92:95], v[154:157], v[170:173], v[92:95]
	v_mfma_f32_16x16x32_bf16 v[84:87], v[162:165], v[170:173], v[84:87]
	v_mfma_f32_16x16x32_bf16 v[76:79], v[154:157], v[178:181], v[76:79]
	v_mfma_f32_16x16x32_bf16 v[72:75], v[162:165], v[178:181], v[72:75]
	v_mfma_f32_16x16x32_bf16 v[64:67], v[154:157], v[186:189], v[64:67]
	v_mfma_f32_16x16x32_bf16 v[56:59], v[162:165], v[186:189], v[56:59]
	v_mfma_f32_16x16x32_bf16 v[52:55], v[154:157], v[196:199], v[52:55]
	v_mfma_f32_16x16x32_bf16 v[48:51], v[162:165], v[196:199], v[48:51]
	v_mfma_f32_16x16x32_bf16 v[92:95], v[158:161], v[174:177], v[92:95]
	v_mfma_f32_16x16x32_bf16 v[84:87], v[166:169], v[174:177], v[84:87]
	v_mfma_f32_16x16x32_bf16 v[76:79], v[158:161], v[182:185], v[76:79]
	v_mfma_f32_16x16x32_bf16 v[72:75], v[166:169], v[182:185], v[72:75]
	v_mfma_f32_16x16x32_bf16 v[64:67], v[158:161], v[190:193], v[64:67]
	v_mfma_f32_16x16x32_bf16 v[56:59], v[166:169], v[190:193], v[56:59]
	v_mfma_f32_16x16x32_bf16 v[52:55], v[158:161], v[200:203], v[52:55]
	v_mfma_f32_16x16x32_bf16 v[48:51], v[166:169], v[200:203], v[48:51]
	s_setprio 0
	s_barrier
	s_add_i32 s34, s58, s28
	v_lshl_add_u64 v[146:147], s[52:53], 0, v[132:133]
	s_mov_b32 m0, s34
	ds_read_b128 v[204:207], v153
	ds_read_b128 v[208:211], v153 offset:1024
	ds_read_b128 v[212:215], v153 offset:2048
	ds_read_b128 v[216:219], v153 offset:3072
	global_load_lds_dwordx4 v[146:147], off
	v_lshl_add_u64 v[220:221], s[52:53], 0, v[128:129]
	s_add_i32 m0, s34, 0x2000
	s_nop 0
	global_load_lds_dwordx4 v[220:221], off
	s_barrier
	s_waitcnt lgkmcnt(0)
	s_setprio 1
	s_waitcnt lgkmcnt(0)
	v_mfma_f32_16x16x32_bf16 v[124:127], v[204:207], v[170:173], v[124:127]
	v_mfma_f32_16x16x32_bf16 v[120:123], v[212:215], v[170:173], v[120:123]
	v_mfma_f32_16x16x32_bf16 v[116:119], v[204:207], v[178:181], v[116:119]
	v_mfma_f32_16x16x32_bf16 v[112:115], v[212:215], v[178:181], v[112:115]
	v_mfma_f32_16x16x32_bf16 v[108:111], v[204:207], v[186:189], v[108:111]
	v_mfma_f32_16x16x32_bf16 v[104:107], v[212:215], v[186:189], v[104:107]
	v_mfma_f32_16x16x32_bf16 v[100:103], v[204:207], v[196:199], v[100:103]
	v_mfma_f32_16x16x32_bf16 v[96:99], v[212:215], v[196:199], v[96:99]
	v_mfma_f32_16x16x32_bf16 v[124:127], v[208:211], v[174:177], v[124:127]
	v_mfma_f32_16x16x32_bf16 v[120:123], v[216:219], v[174:177], v[120:123]
	v_mfma_f32_16x16x32_bf16 v[116:119], v[208:211], v[182:185], v[116:119]
	v_mfma_f32_16x16x32_bf16 v[112:115], v[216:219], v[182:185], v[112:115]
	v_mfma_f32_16x16x32_bf16 v[108:111], v[208:211], v[190:193], v[108:111]
	v_mfma_f32_16x16x32_bf16 v[104:107], v[216:219], v[190:193], v[104:107]
	v_mfma_f32_16x16x32_bf16 v[100:103], v[208:211], v[200:203], v[100:103]
	v_mfma_f32_16x16x32_bf16 v[96:99], v[216:219], v[200:203], v[96:99]
	s_setprio 0
	s_mov_b32 m0, s29
	v_lshl_add_u64 v[222:223], s[56:57], 0, v[134:135]
	s_barrier
	ds_read_b128 v[170:173], v152 offset:16384
	ds_read_b128 v[174:177], v152 offset:17408
	ds_read_b128 v[178:181], v152 offset:18432
	ds_read_b128 v[182:185], v152 offset:19456
	ds_read_b128 v[186:189], v152 offset:20480
	ds_read_b128 v[190:193], v152 offset:21504
	ds_read_b128 v[196:199], v152 offset:22528
	ds_read_b128 v[200:203], v152 offset:23552
	global_load_lds_dwordx4 v[222:223], off
	v_lshl_add_u64 v[224:225], s[56:57], 0, v[130:131]
	s_mov_b32 m0, s30
	s_nop 0
	global_load_lds_dwordx4 v[224:225], off
	s_barrier
	s_waitcnt lgkmcnt(0)
	s_setprio 1
	s_waitcnt lgkmcnt(0)
	v_mfma_f32_16x16x32_bf16 v[32:35], v[154:157], v[170:173], v[32:35]
	v_mfma_f32_16x16x32_bf16 v[24:27], v[162:165], v[170:173], v[24:27]
	v_mfma_f32_16x16x32_bf16 v[20:23], v[154:157], v[178:181], v[20:23]
	v_mfma_f32_16x16x32_bf16 v[16:19], v[162:165], v[178:181], v[16:19]
	v_mfma_f32_16x16x32_bf16 v[12:15], v[154:157], v[186:189], v[12:15]
	v_mfma_f32_16x16x32_bf16 v[8:11], v[162:165], v[186:189], v[8:11]
	v_mfma_f32_16x16x32_bf16 v[4:7], v[154:157], v[196:199], v[4:7]
	v_mfma_f32_16x16x32_bf16 v[0:3], v[162:165], v[196:199], v[0:3]
	v_mfma_f32_16x16x32_bf16 v[32:35], v[158:161], v[174:177], v[32:35]
	v_mfma_f32_16x16x32_bf16 v[24:27], v[166:169], v[174:177], v[24:27]
	v_mfma_f32_16x16x32_bf16 v[20:23], v[158:161], v[182:185], v[20:23]
	v_mfma_f32_16x16x32_bf16 v[16:19], v[166:169], v[182:185], v[16:19]
	v_mfma_f32_16x16x32_bf16 v[12:15], v[158:161], v[190:193], v[12:15]
	v_mfma_f32_16x16x32_bf16 v[8:11], v[166:169], v[190:193], v[8:11]
	v_mfma_f32_16x16x32_bf16 v[4:7], v[158:161], v[200:203], v[4:7]
	v_mfma_f32_16x16x32_bf16 v[0:3], v[166:169], v[200:203], v[0:3]
	s_setprio 0
	s_barrier
	s_add_u32 s34, s52, 0x40000
	s_addc_u32 s35, s53, 0
	s_add_i32 s60, s59, s28
	v_lshl_add_u64 v[154:155], s[34:35], 0, v[132:133]
	s_mov_b32 m0, s60
	s_nop 0
	global_load_lds_dwordx4 v[154:155], off
	v_lshl_add_u64 v[154:155], s[34:35], 0, v[128:129]
	s_add_i32 m0, s60, 0x2000
	s_nop 0
	global_load_lds_dwordx4 v[154:155], off
	s_waitcnt vmcnt(6)
	s_barrier
	s_setprio 1
	v_mfma_f32_16x16x32_bf16 v[88:91], v[204:207], v[170:173], v[88:91]
	v_mfma_f32_16x16x32_bf16 v[80:83], v[212:215], v[170:173], v[80:83]
	v_mfma_f32_16x16x32_bf16 v[68:71], v[204:207], v[178:181], v[68:71]
	v_mfma_f32_16x16x32_bf16 v[60:63], v[212:215], v[178:181], v[60:63]
	v_mfma_f32_16x16x32_bf16 v[44:47], v[204:207], v[186:189], v[44:47]
	v_mfma_f32_16x16x32_bf16 v[40:43], v[212:215], v[186:189], v[40:43]
	v_mfma_f32_16x16x32_bf16 v[36:39], v[204:207], v[196:199], v[36:39]
	v_mfma_f32_16x16x32_bf16 v[28:31], v[212:215], v[196:199], v[28:31]
	v_mfma_f32_16x16x32_bf16 v[88:91], v[208:211], v[174:177], v[88:91]
	v_mfma_f32_16x16x32_bf16 v[80:83], v[216:219], v[174:177], v[80:83]
	v_mfma_f32_16x16x32_bf16 v[68:71], v[208:211], v[182:185], v[68:71]
	v_mfma_f32_16x16x32_bf16 v[60:63], v[216:219], v[182:185], v[60:63]
	v_mfma_f32_16x16x32_bf16 v[44:47], v[208:211], v[190:193], v[44:47]
	v_mfma_f32_16x16x32_bf16 v[40:43], v[216:219], v[190:193], v[40:43]
	v_mfma_f32_16x16x32_bf16 v[36:39], v[208:211], v[200:203], v[36:39]
	v_mfma_f32_16x16x32_bf16 v[28:31], v[216:219], v[200:203], v[28:31]
	s_setprio 0
	s_add_i32 s60, 0, 0x18000
	v_add_u32_e32 v166, s60, v149
	s_barrier
	ds_read_b128 v[154:157], v166
	ds_read_b128 v[158:161], v166 offset:1024
	ds_read_b128 v[162:165], v166 offset:2048
	ds_read_b128 v[166:169], v166 offset:3072
	s_add_u32 s34, s56, 0x40000
	s_addc_u32 s35, s57, 0
	s_mov_b32 m0, s31
	v_lshl_add_u64 v[204:205], s[34:35], 0, v[134:135]
	ds_read_b128 v[170:173], v152 offset:32768
	ds_read_b128 v[174:177], v152 offset:33792
	ds_read_b128 v[178:181], v152 offset:34816
	ds_read_b128 v[182:185], v152 offset:35840
	ds_read_b128 v[186:189], v152 offset:36864
	ds_read_b128 v[190:193], v152 offset:37888
	ds_read_b128 v[196:199], v152 offset:38912
	ds_read_b128 v[200:203], v152 offset:39936
	global_load_lds_dwordx4 v[204:205], off
	v_lshl_add_u64 v[204:205], s[34:35], 0, v[130:131]
	s_mov_b32 m0, s33
	s_nop 0
	global_load_lds_dwordx4 v[204:205], off
	s_waitcnt lgkmcnt(8)
	s_barrier
	s_waitcnt lgkmcnt(0)
	s_setprio 1
	s_waitcnt lgkmcnt(0)
	v_mfma_f32_16x16x32_bf16 v[92:95], v[154:157], v[170:173], v[92:95]
	v_mfma_f32_16x16x32_bf16 v[84:87], v[162:165], v[170:173], v[84:87]
	v_mfma_f32_16x16x32_bf16 v[76:79], v[154:157], v[178:181], v[76:79]
	v_mfma_f32_16x16x32_bf16 v[72:75], v[162:165], v[178:181], v[72:75]
	v_mfma_f32_16x16x32_bf16 v[64:67], v[154:157], v[186:189], v[64:67]
	v_mfma_f32_16x16x32_bf16 v[56:59], v[162:165], v[186:189], v[56:59]
	v_mfma_f32_16x16x32_bf16 v[52:55], v[154:157], v[196:199], v[52:55]
	v_mfma_f32_16x16x32_bf16 v[48:51], v[162:165], v[196:199], v[48:51]
	v_mfma_f32_16x16x32_bf16 v[92:95], v[158:161], v[174:177], v[92:95]
	v_mfma_f32_16x16x32_bf16 v[84:87], v[166:169], v[174:177], v[84:87]
	v_mfma_f32_16x16x32_bf16 v[76:79], v[158:161], v[182:185], v[76:79]
	v_mfma_f32_16x16x32_bf16 v[72:75], v[166:169], v[182:185], v[72:75]
	v_mfma_f32_16x16x32_bf16 v[64:67], v[158:161], v[190:193], v[64:67]
	v_mfma_f32_16x16x32_bf16 v[56:59], v[166:169], v[190:193], v[56:59]
	v_mfma_f32_16x16x32_bf16 v[52:55], v[158:161], v[200:203], v[52:55]
	v_mfma_f32_16x16x32_bf16 v[48:51], v[166:169], v[200:203], v[48:51]
	s_setprio 0
	s_barrier
	s_add_i32 s56, 0, 0x1c000
	s_add_i32 s34, s60, s28
	v_add_u32_e32 v195, s56, v149
	v_lshl_add_u64 v[146:147], v[146:147], 0, s[10:11]
	s_mov_b32 m0, s34
	ds_read_b128 v[204:207], v195
	ds_read_b128 v[208:211], v195 offset:1024
	ds_read_b128 v[212:215], v195 offset:2048
	ds_read_b128 v[216:219], v195 offset:3072
	global_load_lds_dwordx4 v[146:147], off
	v_lshl_add_u64 v[146:147], v[220:221], 0, s[10:11]
	s_add_i32 m0, s34, 0x2000
	s_nop 0
	global_load_lds_dwordx4 v[146:147], off
	s_barrier
	s_waitcnt lgkmcnt(0)
	s_setprio 1
	s_waitcnt lgkmcnt(0)
	v_mfma_f32_16x16x32_bf16 v[124:127], v[204:207], v[170:173], v[124:127]
	v_mfma_f32_16x16x32_bf16 v[120:123], v[212:215], v[170:173], v[120:123]
	v_mfma_f32_16x16x32_bf16 v[116:119], v[204:207], v[178:181], v[116:119]
	v_mfma_f32_16x16x32_bf16 v[112:115], v[212:215], v[178:181], v[112:115]
	v_mfma_f32_16x16x32_bf16 v[108:111], v[204:207], v[186:189], v[108:111]
	v_mfma_f32_16x16x32_bf16 v[104:107], v[212:215], v[186:189], v[104:107]
	v_mfma_f32_16x16x32_bf16 v[100:103], v[204:207], v[196:199], v[100:103]
	v_mfma_f32_16x16x32_bf16 v[96:99], v[212:215], v[196:199], v[96:99]
	v_mfma_f32_16x16x32_bf16 v[124:127], v[208:211], v[174:177], v[124:127]
	v_mfma_f32_16x16x32_bf16 v[120:123], v[216:219], v[174:177], v[120:123]
	v_mfma_f32_16x16x32_bf16 v[116:119], v[208:211], v[182:185], v[116:119]
	v_mfma_f32_16x16x32_bf16 v[112:115], v[216:219], v[182:185], v[112:115]
	v_mfma_f32_16x16x32_bf16 v[108:111], v[208:211], v[190:193], v[108:111]
	v_mfma_f32_16x16x32_bf16 v[104:107], v[216:219], v[190:193], v[104:107]
	v_mfma_f32_16x16x32_bf16 v[100:103], v[208:211], v[200:203], v[100:103]
	v_mfma_f32_16x16x32_bf16 v[96:99], v[216:219], v[200:203], v[96:99]
	s_setprio 0
	s_mov_b32 m0, s42
	v_lshl_add_u64 v[146:147], v[222:223], 0, s[10:11]
	s_barrier
	ds_read_b128 v[170:173], v152 offset:49152
	ds_read_b128 v[174:177], v152 offset:50176
	ds_read_b128 v[178:181], v152 offset:51200
	ds_read_b128 v[182:185], v152 offset:52224
	ds_read_b128 v[186:189], v152 offset:53248
	ds_read_b128 v[190:193], v152 offset:54272
	ds_read_b128 v[196:199], v152 offset:55296
	ds_read_b128 v[200:203], v152 offset:56320
	global_load_lds_dwordx4 v[146:147], off
	v_lshl_add_u64 v[146:147], v[224:225], 0, s[10:11]
	s_mov_b32 m0, s43
	s_nop 0
	global_load_lds_dwordx4 v[146:147], off
	s_barrier
	s_waitcnt lgkmcnt(0)
	s_setprio 1
	s_waitcnt lgkmcnt(0)
	v_mfma_f32_16x16x32_bf16 v[32:35], v[154:157], v[170:173], v[32:35]
	v_mfma_f32_16x16x32_bf16 v[24:27], v[162:165], v[170:173], v[24:27]
	v_mfma_f32_16x16x32_bf16 v[20:23], v[154:157], v[178:181], v[20:23]
	v_mfma_f32_16x16x32_bf16 v[16:19], v[162:165], v[178:181], v[16:19]
	v_mfma_f32_16x16x32_bf16 v[12:15], v[154:157], v[186:189], v[12:15]
	v_mfma_f32_16x16x32_bf16 v[8:11], v[162:165], v[186:189], v[8:11]
	v_mfma_f32_16x16x32_bf16 v[4:7], v[154:157], v[196:199], v[4:7]
	v_mfma_f32_16x16x32_bf16 v[0:3], v[162:165], v[196:199], v[0:3]
	v_mfma_f32_16x16x32_bf16 v[32:35], v[158:161], v[174:177], v[32:35]
	v_mfma_f32_16x16x32_bf16 v[24:27], v[166:169], v[174:177], v[24:27]
	v_mfma_f32_16x16x32_bf16 v[20:23], v[158:161], v[182:185], v[20:23]
	v_mfma_f32_16x16x32_bf16 v[16:19], v[166:169], v[182:185], v[16:19]
	v_mfma_f32_16x16x32_bf16 v[12:15], v[158:161], v[190:193], v[12:15]
	v_mfma_f32_16x16x32_bf16 v[8:11], v[166:169], v[190:193], v[8:11]
	v_mfma_f32_16x16x32_bf16 v[4:7], v[158:161], v[200:203], v[4:7]
	v_mfma_f32_16x16x32_bf16 v[0:3], v[166:169], v[200:203], v[0:3]
	s_setprio 0
	s_barrier
	s_add_u32 s34, s52, 0x40080
	s_addc_u32 s35, s53, 0
	s_add_i32 s52, s56, s28
	v_lshl_add_u64 v[146:147], s[34:35], 0, v[132:133]
	s_mov_b32 m0, s52
	s_nop 0
	global_load_lds_dwordx4 v[146:147], off
	v_lshl_add_u64 v[146:147], s[34:35], 0, v[128:129]
	s_add_i32 m0, s52, 0x2000
	s_nop 0
	global_load_lds_dwordx4 v[146:147], off
	s_waitcnt vmcnt(6)
	s_barrier
	s_setprio 1
	v_mfma_f32_16x16x32_bf16 v[88:91], v[204:207], v[170:173], v[88:91]
	v_mfma_f32_16x16x32_bf16 v[80:83], v[212:215], v[170:173], v[80:83]
	v_mfma_f32_16x16x32_bf16 v[68:71], v[204:207], v[178:181], v[68:71]
	v_mfma_f32_16x16x32_bf16 v[60:63], v[212:215], v[178:181], v[60:63]
	v_mfma_f32_16x16x32_bf16 v[44:47], v[204:207], v[186:189], v[44:47]
	v_mfma_f32_16x16x32_bf16 v[40:43], v[212:215], v[186:189], v[40:43]
	v_mfma_f32_16x16x32_bf16 v[36:39], v[204:207], v[196:199], v[36:39]
	v_mfma_f32_16x16x32_bf16 v[28:31], v[212:215], v[196:199], v[28:31]
	v_mfma_f32_16x16x32_bf16 v[88:91], v[208:211], v[174:177], v[88:91]
	v_mfma_f32_16x16x32_bf16 v[80:83], v[216:219], v[174:177], v[80:83]
	v_mfma_f32_16x16x32_bf16 v[68:71], v[208:211], v[182:185], v[68:71]
	v_mfma_f32_16x16x32_bf16 v[60:63], v[216:219], v[182:185], v[60:63]
	v_mfma_f32_16x16x32_bf16 v[44:47], v[208:211], v[190:193], v[44:47]
	v_mfma_f32_16x16x32_bf16 v[40:43], v[216:219], v[190:193], v[40:43]
	v_mfma_f32_16x16x32_bf16 v[36:39], v[208:211], v[200:203], v[36:39]
	v_mfma_f32_16x16x32_bf16 v[28:31], v[216:219], v[200:203], v[28:31]
	s_setprio 0
	s_add_i32 s91, s91, 2
	s_add_u32 s24, s24, 0x100
	s_addc_u32 s25, s25, 0
	s_add_u32 s89, s89, 0x100
	s_addc_u32 s90, s90, 0
	s_cmp_gt_u32 s91, 13
	s_barrier
	s_cbranch_scc0 .LBB0_133
	s_branch .Lgk_exit
.Lgk_b:
	ds_read_b128 v[154:157], v151
	ds_read_b128 v[158:161], v151 offset:1024
	ds_read_b128 v[162:165], v151 offset:2048
	ds_read_b128 v[166:169], v151 offset:3072
	s_add_u32 s34, s24, 0xfffc0080
	s_addc_u32 s35, s25, -1
	s_cmp_eq_u32 s91, 12
	s_cselect_b32 s57, s15, s35
	s_cselect_b32 s56, s17, s34
	s_cselect_b32 s53, s9, s90
	s_cselect_b32 s52, s19, s89
	v_lshl_add_u64 v[146:147], s[24:25], 0, v[138:139]
	s_add_i32 m0, s29, 0xc000
	ds_read_b128 v[170:173], v152
	ds_read_b128 v[174:177], v152 offset:1024
	ds_read_b128 v[178:181], v152 offset:2048
	ds_read_b128 v[182:185], v152 offset:3072
	ds_read_b128 v[186:189], v152 offset:4096
	ds_read_b128 v[190:193], v152 offset:5120
	ds_read_b128 v[196:199], v152 offset:6144
	ds_read_b128 v[200:203], v152 offset:7168
	global_load_lds_dwordx4 v[146:147], off
	v_lshl_add_u64 v[146:147], s[24:25], 0, v[140:141]
	s_add_i32 m0, s29, 0xe000
	s_nop 0
	global_load_lds_dwordx4 v[146:147], off
	s_waitcnt lgkmcnt(8)
	s_barrier
	s_waitcnt lgkmcnt(0)
	s_setprio 2
	s_waitcnt lgkmcnt(0)
	v_mfma_f32_16x16x32_bf16 v[92:95], v[154:157], v[170:173], v[92:95]
	v_mfma_f32_16x16x32_bf16 v[84:87], v[162:165], v[170:173], v[84:87]
	v_mfma_f32_16x16x32_bf16 v[76:79], v[154:157], v[178:181], v[76:79]
	v_mfma_f32_16x16x32_bf16 v[72:75], v[162:165], v[178:181], v[72:75]
	v_mfma_f32_16x16x32_bf16 v[64:67], v[154:157], v[186:189], v[64:67]
	v_mfma_f32_16x16x32_bf16 v[56:59], v[162:165], v[186:189], v[56:59]
	v_mfma_f32_16x16x32_bf16 v[52:55], v[154:157], v[196:199], v[52:55]
	v_mfma_f32_16x16x32_bf16 v[48:51], v[162:165], v[196:199], v[48:51]
	v_mfma_f32_16x16x32_bf16 v[92:95], v[158:161], v[174:177], v[92:95]
	v_mfma_f32_16x16x32_bf16 v[84:87], v[166:169], v[174:177], v[84:87]
	v_mfma_f32_16x16x32_bf16 v[76:79], v[158:161], v[182:185], v[76:79]
	v_mfma_f32_16x16x32_bf16 v[72:75], v[166:169], v[182:185], v[72:75]
	v_mfma_f32_16x16x32_bf16 v[64:67], v[158:161], v[190:193], v[64:67]
	v_mfma_f32_16x16x32_bf16 v[56:59], v[166:169], v[190:193], v[56:59]
	v_mfma_f32_16x16x32_bf16 v[52:55], v[158:161], v[200:203], v[52:55]
	v_mfma_f32_16x16x32_bf16 v[48:51], v[166:169], v[200:203], v[48:51]
	s_setprio 1
	s_barrier
	s_add_i32 s34, s58, s28
	v_lshl_add_u64 v[146:147], s[52:53], 0, v[132:133]
	s_mov_b32 m0, s34
	ds_read_b128 v[204:207], v153
	ds_read_b128 v[208:211], v153 offset:1024
	ds_read_b128 v[212:215], v153 offset:2048
	ds_read_b128 v[216:219], v153 offset:3072
	global_load_lds_dwordx4 v[146:147], off
	v_lshl_add_u64 v[220:221], s[52:53], 0, v[128:129]
	s_add_i32 m0, s34, 0x2000
	s_nop 0
	global_load_lds_dwordx4 v[220:221], off
	s_barrier
	s_waitcnt lgkmcnt(0)
	s_setprio 2
	s_waitcnt lgkmcnt(0)
	v_mfma_f32_16x16x32_bf16 v[124:127], v[204:207], v[170:173], v[124:127]
	v_mfma_f32_16x16x32_bf16 v[120:123], v[212:215], v[170:173], v[120:123]
	v_mfma_f32_16x16x32_bf16 v[116:119], v[204:207], v[178:181], v[116:119]
	v_mfma_f32_16x16x32_bf16 v[112:115], v[212:215], v[178:181], v[112:115]
	v_mfma_f32_16x16x32_bf16 v[108:111], v[204:207], v[186:189], v[108:111]
	v_mfma_f32_16x16x32_bf16 v[104:107], v[212:215], v[186:189], v[104:107]
	v_mfma_f32_16x16x32_bf16 v[100:103], v[204:207], v[196:199], v[100:103]
	v_mfma_f32_16x16x32_bf16 v[96:99], v[212:215], v[196:199], v[96:99]
	v_mfma_f32_16x16x32_bf16 v[124:127], v[208:211], v[174:177], v[124:127]
	v_mfma_f32_16x16x32_bf16 v[120:123], v[216:219], v[174:177], v[120:123]
	v_mfma_f32_16x16x32_bf16 v[116:119], v[208:211], v[182:185], v[116:119]
	v_mfma_f32_16x16x32_bf16 v[112:115], v[216:219], v[182:185], v[112:115]
	v_mfma_f32_16x16x32_bf16 v[108:111], v[208:211], v[190:193], v[108:111]
	v_mfma_f32_16x16x32_bf16 v[104:107], v[216:219], v[190:193], v[104:107]
	v_mfma_f32_16x16x32_bf16 v[100:103], v[208:211], v[200:203], v[100:103]
	v_mfma_f32_16x16x32_bf16 v[96:99], v[216:219], v[200:203], v[96:99]
	s_setprio 1
	s_mov_b32 m0, s29
	v_lshl_add_u64 v[222:223], s[56:57], 0, v[134:135]
	s_barrier
	ds_read_b128 v[170:173], v152 offset:16384
	ds_read_b128 v[174:177], v152 offset:17408
	ds_read_b128 v[178:181], v152 offset:18432
	ds_read_b128 v[182:185], v152 offset:19456
	ds_read_b128 v[186:189], v152 offset:20480
	ds_read_b128 v[190:193], v152 offset:21504
	ds_read_b128 v[196:199], v152 offset:22528
	ds_read_b128 v[200:203], v152 offset:23552
	global_load_lds_dwordx4 v[222:223], off
	v_lshl_add_u64 v[224:225], s[56:57], 0, v[130:131]
	s_mov_b32 m0, s30
	s_nop 0
	global_load_lds_dwordx4 v[224:225], off
	s_barrier
	s_waitcnt lgkmcnt(0)
	s_setprio 2
	s_waitcnt lgkmcnt(0)
	v_mfma_f32_16x16x32_bf16 v[32:35], v[154:157], v[170:173], v[32:35]
	v_mfma_f32_16x16x32_bf16 v[24:27], v[162:165], v[170:173], v[24:27]
	v_mfma_f32_16x16x32_bf16 v[20:23], v[154:157], v[178:181], v[20:23]
	v_mfma_f32_16x16x32_bf16 v[16:19], v[162:165], v[178:181], v[16:19]
	v_mfma_f32_16x16x32_bf16 v[12:15], v[154:157], v[186:189], v[12:15]
	v_mfma_f32_16x16x32_bf16 v[8:11], v[162:165], v[186:189], v[8:11]
	v_mfma_f32_16x16x32_bf16 v[4:7], v[154:157], v[196:199], v[4:7]
	v_mfma_f32_16x16x32_bf16 v[0:3], v[162:165], v[196:199], v[0:3]
	v_mfma_f32_16x16x32_bf16 v[32:35], v[158:161], v[174:177], v[32:35]
	v_mfma_f32_16x16x32_bf16 v[24:27], v[166:169], v[174:177], v[24:27]
	v_mfma_f32_16x16x32_bf16 v[20:23], v[158:161], v[182:185], v[20:23]
	v_mfma_f32_16x16x32_bf16 v[16:19], v[166:169], v[182:185], v[16:19]
	v_mfma_f32_16x16x32_bf16 v[12:15], v[158:161], v[190:193], v[12:15]
	v_mfma_f32_16x16x32_bf16 v[8:11], v[166:169], v[190:193], v[8:11]
	v_mfma_f32_16x16x32_bf16 v[4:7], v[158:161], v[200:203], v[4:7]
	v_mfma_f32_16x16x32_bf16 v[0:3], v[166:169], v[200:203], v[0:3]
	s_setprio 1
	s_barrier
	s_add_u32 s34, s52, 0x40000
	s_addc_u32 s35, s53, 0
	s_add_i32 s60, s59, s28
	v_lshl_add_u64 v[154:155], s[34:35], 0, v[132:133]
	s_mov_b32 m0, s60
	s_nop 0
	global_load_lds_dwordx4 v[154:155], off
	v_lshl_add_u64 v[154:155], s[34:35], 0, v[128:129]
	s_add_i32 m0, s60, 0x2000
	s_nop 0
	global_load_lds_dwordx4 v[154:155], off
	s_waitcnt vmcnt(6)
	s_barrier
	s_setprio 2
	v_mfma_f32_16x16x32_bf16 v[88:91], v[204:207], v[170:173], v[88:91]
	v_mfma_f32_16x16x32_bf16 v[80:83], v[212:215], v[170:173], v[80:83]
	v_mfma_f32_16x16x32_bf16 v[68:71], v[204:207], v[178:181], v[68:71]
	v_mfma_f32_16x16x32_bf16 v[60:63], v[212:215], v[178:181], v[60:63]
	v_mfma_f32_16x16x32_bf16 v[44:47], v[204:207], v[186:189], v[44:47]
	v_mfma_f32_16x16x32_bf16 v[40:43], v[212:215], v[186:189], v[40:43]
	v_mfma_f32_16x16x32_bf16 v[36:39], v[204:207], v[196:199], v[36:39]
	v_mfma_f32_16x16x32_bf16 v[28:31], v[212:215], v[196:199], v[28:31]
	v_mfma_f32_16x16x32_bf16 v[88:91], v[208:211], v[174:177], v[88:91]
	v_mfma_f32_16x16x32_bf16 v[80:83], v[216:219], v[174:177], v[80:83]
	v_mfma_f32_16x16x32_bf16 v[68:71], v[208:211], v[182:185], v[68:71]
	v_mfma_f32_16x16x32_bf16 v[60:63], v[216:219], v[182:185], v[60:63]
	v_mfma_f32_16x16x32_bf16 v[44:47], v[208:211], v[190:193], v[44:47]
	v_mfma_f32_16x16x32_bf16 v[40:43], v[216:219], v[190:193], v[40:43]
	v_mfma_f32_16x16x32_bf16 v[36:39], v[208:211], v[200:203], v[36:39]
	v_mfma_f32_16x16x32_bf16 v[28:31], v[216:219], v[200:203], v[28:31]
	s_setprio 1
	s_add_i32 s60, 0, 0x18000
	v_add_u32_e32 v166, s60, v149
	s_barrier
	ds_read_b128 v[154:157], v166
	ds_read_b128 v[158:161], v166 offset:1024
	ds_read_b128 v[162:165], v166 offset:2048
	ds_read_b128 v[166:169], v166 offset:3072
	s_add_u32 s34, s56, 0x40000
	s_addc_u32 s35, s57, 0
	s_mov_b32 m0, s31
	v_lshl_add_u64 v[204:205], s[34:35], 0, v[134:135]
	ds_read_b128 v[170:173], v152 offset:32768
	ds_read_b128 v[174:177], v152 offset:33792
	ds_read_b128 v[178:181], v152 offset:34816
	ds_read_b128 v[182:185], v152 offset:35840
	ds_read_b128 v[186:189], v152 offset:36864
	ds_read_b128 v[190:193], v152 offset:37888
	ds_read_b128 v[196:199], v152 offset:38912
	ds_read_b128 v[200:203], v152 offset:39936
	global_load_lds_dwordx4 v[204:205], off
	v_lshl_add_u64 v[204:205], s[34:35], 0, v[130:131]
	s_mov_b32 m0, s33
	s_nop 0
	global_load_lds_dwordx4 v[204:205], off
	s_waitcnt lgkmcnt(8)
	s_barrier
	s_waitcnt lgkmcnt(0)
	s_setprio 2
	s_waitcnt lgkmcnt(0)
	v_mfma_f32_16x16x32_bf16 v[92:95], v[154:157], v[170:173], v[92:95]
	v_mfma_f32_16x16x32_bf16 v[84:87], v[162:165], v[170:173], v[84:87]
	v_mfma_f32_16x16x32_bf16 v[76:79], v[154:157], v[178:181], v[76:79]
	v_mfma_f32_16x16x32_bf16 v[72:75], v[162:165], v[178:181], v[72:75]
	v_mfma_f32_16x16x32_bf16 v[64:67], v[154:157], v[186:189], v[64:67]
	v_mfma_f32_16x16x32_bf16 v[56:59], v[162:165], v[186:189], v[56:59]
	v_mfma_f32_16x16x32_bf16 v[52:55], v[154:157], v[196:199], v[52:55]
	v_mfma_f32_16x16x32_bf16 v[48:51], v[162:165], v[196:199], v[48:51]
	v_mfma_f32_16x16x32_bf16 v[92:95], v[158:161], v[174:177], v[92:95]
	v_mfma_f32_16x16x32_bf16 v[84:87], v[166:169], v[174:177], v[84:87]
	v_mfma_f32_16x16x32_bf16 v[76:79], v[158:161], v[182:185], v[76:79]
	v_mfma_f32_16x16x32_bf16 v[72:75], v[166:169], v[182:185], v[72:75]
	v_mfma_f32_16x16x32_bf16 v[64:67], v[158:161], v[190:193], v[64:67]
	v_mfma_f32_16x16x32_bf16 v[56:59], v[166:169], v[190:193], v[56:59]
	v_mfma_f32_16x16x32_bf16 v[52:55], v[158:161], v[200:203], v[52:55]
	v_mfma_f32_16x16x32_bf16 v[48:51], v[166:169], v[200:203], v[48:51]
	s_setprio 1
	s_barrier
	s_add_i32 s56, 0, 0x1c000
	s_add_i32 s34, s60, s28
	v_add_u32_e32 v195, s56, v149
	v_lshl_add_u64 v[146:147], v[146:147], 0, s[10:11]
	s_mov_b32 m0, s34
	ds_read_b128 v[204:207], v195
	ds_read_b128 v[208:211], v195 offset:1024
	ds_read_b128 v[212:215], v195 offset:2048
	ds_read_b128 v[216:219], v195 offset:3072
	global_load_lds_dwordx4 v[146:147], off
	v_lshl_add_u64 v[146:147], v[220:221], 0, s[10:11]
	s_add_i32 m0, s34, 0x2000
	s_nop 0
	global_load_lds_dwordx4 v[146:147], off
	s_barrier
	s_waitcnt lgkmcnt(0)
	s_setprio 2
	s_waitcnt lgkmcnt(0)
	v_mfma_f32_16x16x32_bf16 v[124:127], v[204:207], v[170:173], v[124:127]
	v_mfma_f32_16x16x32_bf16 v[120:123], v[212:215], v[170:173], v[120:123]
	v_mfma_f32_16x16x32_bf16 v[116:119], v[204:207], v[178:181], v[116:119]
	v_mfma_f32_16x16x32_bf16 v[112:115], v[212:215], v[178:181], v[112:115]
	v_mfma_f32_16x16x32_bf16 v[108:111], v[204:207], v[186:189], v[108:111]
	v_mfma_f32_16x16x32_bf16 v[104:107], v[212:215], v[186:189], v[104:107]
	v_mfma_f32_16x16x32_bf16 v[100:103], v[204:207], v[196:199], v[100:103]
	v_mfma_f32_16x16x32_bf16 v[96:99], v[212:215], v[196:199], v[96:99]
	v_mfma_f32_16x16x32_bf16 v[124:127], v[208:211], v[174:177], v[124:127]
	v_mfma_f32_16x16x32_bf16 v[120:123], v[216:219], v[174:177], v[120:123]
	v_mfma_f32_16x16x32_bf16 v[116:119], v[208:211], v[182:185], v[116:119]
	v_mfma_f32_16x16x32_bf16 v[112:115], v[216:219], v[182:185], v[112:115]
	v_mfma_f32_16x16x32_bf16 v[108:111], v[208:211], v[190:193], v[108:111]
	v_mfma_f32_16x16x32_bf16 v[104:107], v[216:219], v[190:193], v[104:107]
	v_mfma_f32_16x16x32_bf16 v[100:103], v[208:211], v[200:203], v[100:103]
	v_mfma_f32_16x16x32_bf16 v[96:99], v[216:219], v[200:203], v[96:99]
	s_setprio 1
	s_mov_b32 m0, s42
	v_lshl_add_u64 v[146:147], v[222:223], 0, s[10:11]
	s_barrier
	ds_read_b128 v[170:173], v152 offset:49152
	ds_read_b128 v[174:177], v152 offset:50176
	ds_read_b128 v[178:181], v152 offset:51200
	ds_read_b128 v[182:185], v152 offset:52224
	ds_read_b128 v[186:189], v152 offset:53248
	ds_read_b128 v[190:193], v152 offset:54272
	ds_read_b128 v[196:199], v152 offset:55296
	ds_read_b128 v[200:203], v152 offset:56320
	global_load_lds_dwordx4 v[146:147], off
	v_lshl_add_u64 v[146:147], v[224:225], 0, s[10:11]
	s_mov_b32 m0, s43
	s_nop 0
	global_load_lds_dwordx4 v[146:147], off
	s_barrier
	s_waitcnt lgkmcnt(0)
	s_setprio 2
	s_waitcnt lgkmcnt(0)
	v_mfma_f32_16x16x32_bf16 v[32:35], v[154:157], v[170:173], v[32:35]
	v_mfma_f32_16x16x32_bf16 v[24:27], v[162:165], v[170:173], v[24:27]
	v_mfma_f32_16x16x32_bf16 v[20:23], v[154:157], v[178:181], v[20:23]
	v_mfma_f32_16x16x32_bf16 v[16:19], v[162:165], v[178:181], v[16:19]
	v_mfma_f32_16x16x32_bf16 v[12:15], v[154:157], v[186:189], v[12:15]
	v_mfma_f32_16x16x32_bf16 v[8:11], v[162:165], v[186:189], v[8:11]
	v_mfma_f32_16x16x32_bf16 v[4:7], v[154:157], v[196:199], v[4:7]
	v_mfma_f32_16x16x32_bf16 v[0:3], v[162:165], v[196:199], v[0:3]
	v_mfma_f32_16x16x32_bf16 v[32:35], v[158:161], v[174:177], v[32:35]
	v_mfma_f32_16x16x32_bf16 v[24:27], v[166:169], v[174:177], v[24:27]
	v_mfma_f32_16x16x32_bf16 v[20:23], v[158:161], v[182:185], v[20:23]
	v_mfma_f32_16x16x32_bf16 v[16:19], v[166:169], v[182:185], v[16:19]
	v_mfma_f32_16x16x32_bf16 v[12:15], v[158:161], v[190:193], v[12:15]
	v_mfma_f32_16x16x32_bf16 v[8:11], v[166:169], v[190:193], v[8:11]
	v_mfma_f32_16x16x32_bf16 v[4:7], v[158:161], v[200:203], v[4:7]
	v_mfma_f32_16x16x32_bf16 v[0:3], v[166:169], v[200:203], v[0:3]
	s_setprio 1
	s_barrier
	s_add_u32 s34, s52, 0x40080
	s_addc_u32 s35, s53, 0
	s_add_i32 s52, s56, s28
	v_lshl_add_u64 v[146:147], s[34:35], 0, v[132:133]
	s_mov_b32 m0, s52
	s_nop 0
	global_load_lds_dwordx4 v[146:147], off
	v_lshl_add_u64 v[146:147], s[34:35], 0, v[128:129]
	s_add_i32 m0, s52, 0x2000
	s_nop 0
	global_load_lds_dwordx4 v[146:147], off
	s_waitcnt vmcnt(6)
	s_barrier
	s_setprio 2
	v_mfma_f32_16x16x32_bf16 v[88:91], v[204:207], v[170:173], v[88:91]
	v_mfma_f32_16x16x32_bf16 v[80:83], v[212:215], v[170:173], v[80:83]
	v_mfma_f32_16x16x32_bf16 v[68:71], v[204:207], v[178:181], v[68:71]
	v_mfma_f32_16x16x32_bf16 v[60:63], v[212:215], v[178:181], v[60:63]
	v_mfma_f32_16x16x32_bf16 v[44:47], v[204:207], v[186:189], v[44:47]
	v_mfma_f32_16x16x32_bf16 v[40:43], v[212:215], v[186:189], v[40:43]
	v_mfma_f32_16x16x32_bf16 v[36:39], v[204:207], v[196:199], v[36:39]
	v_mfma_f32_16x16x32_bf16 v[28:31], v[212:215], v[196:199], v[28:31]
	v_mfma_f32_16x16x32_bf16 v[88:91], v[208:211], v[174:177], v[88:91]
	v_mfma_f32_16x16x32_bf16 v[80:83], v[216:219], v[174:177], v[80:83]
	v_mfma_f32_16x16x32_bf16 v[68:71], v[208:211], v[182:185], v[68:71]
	v_mfma_f32_16x16x32_bf16 v[60:63], v[216:219], v[182:185], v[60:63]
	v_mfma_f32_16x16x32_bf16 v[44:47], v[208:211], v[190:193], v[44:47]
	v_mfma_f32_16x16x32_bf16 v[40:43], v[216:219], v[190:193], v[40:43]
	v_mfma_f32_16x16x32_bf16 v[36:39], v[208:211], v[200:203], v[36:39]
	v_mfma_f32_16x16x32_bf16 v[28:31], v[216:219], v[200:203], v[28:31]
	s_setprio 1
	s_add_i32 s91, s91, 2
	s_add_u32 s24, s24, 0x100
	s_addc_u32 s25, s25, 0
	s_add_u32 s89, s89, 0x100
	s_addc_u32 s90, s90, 0
	s_cmp_gt_u32 s91, 13
	s_barrier
	s_cbranch_scc0 .Lgk_b
	s_setprio 0
.Lgk_exit:
	v_lshl_add_u32 v146, s16, 8, v148
	s_cmp_lg_u32 s14, 18
	s_mov_b64 s[16:17], -1
	s_cbranch_scc0 .LBB0_136
	v_lshl_or_b32 v154, s14, 8, v150
	v_ashrrev_i32_e32 v155, 31, v154
	v_mov_b64_e32 v[158:159], s[26:27]
	v_mad_i64_i32 v[156:157], s[14:15], v146, s88, v[158:159]
	v_lshlrev_b64 v[160:161], 1, v[154:155]
	v_cvt_pk_bf16_f32 v124, v124, v125
	v_cvt_pk_bf16_f32 v125, v126, v127
	v_cvt_pk_bf16_f32 v126, v120, v121
	v_or_b32_e32 v120, 16, v146
	v_lshl_add_u64 v[162:163], v[156:157], 0, v[160:161]
	v_cvt_pk_bf16_f32 v127, v122, v123
	v_mad_i64_i32 v[120:121], s[14:15], v120, s88, v[158:159]
	v_cvt_pk_bf16_f32 v116, v116, v117
	v_cvt_pk_bf16_f32 v117, v118, v119
	v_cvt_pk_bf16_f32 v118, v112, v113
	v_or_b32_e32 v112, 32, v146
	global_store_dwordx4 v[162:163], v[124:127], off offset:256 nt
	v_cvt_pk_bf16_f32 v119, v114, v115
	v_mad_i64_i32 v[112:113], s[14:15], v112, s88, v[158:159]
	v_lshl_add_u64 v[124:125], v[120:121], 0, v[160:161]
	v_cvt_pk_bf16_f32 v108, v108, v109
	v_cvt_pk_bf16_f32 v109, v110, v111
	v_cvt_pk_bf16_f32 v110, v104, v105
	v_or_b32_e32 v104, 48, v146
	global_store_dwordx4 v[124:125], v[116:119], off offset:256 nt
	v_cvt_pk_bf16_f32 v111, v106, v107
	v_mad_i64_i32 v[104:105], s[14:15], v104, s88, v[158:159]
	v_lshl_add_u64 v[116:117], v[112:113], 0, v[160:161]
	v_cvt_pk_bf16_f32 v100, v100, v101
	v_cvt_pk_bf16_f32 v101, v102, v103
	v_cvt_pk_bf16_f32 v102, v96, v97
	v_add_u32_e32 v96, 0x80, v146
	global_store_dwordx4 v[116:117], v[108:111], off offset:256 nt
	v_cvt_pk_bf16_f32 v103, v98, v99
	v_mad_i64_i32 v[96:97], s[14:15], v96, s88, v[158:159]
	v_lshl_add_u64 v[108:109], v[104:105], 0, v[160:161]
	v_cvt_pk_bf16_f32 v88, v88, v89
	v_cvt_pk_bf16_f32 v89, v90, v91
	v_cvt_pk_bf16_f32 v90, v80, v81
	v_add_u32_e32 v80, 0x90, v146
	global_store_dwordx4 v[108:109], v[100:103], off offset:256 nt
	v_cvt_pk_bf16_f32 v91, v82, v83
	v_mad_i64_i32 v[80:81], s[14:15], v80, s88, v[158:159]
	v_lshl_add_u64 v[100:101], v[96:97], 0, v[160:161]
	v_cvt_pk_bf16_f32 v68, v68, v69
	v_cvt_pk_bf16_f32 v69, v70, v71
	v_cvt_pk_bf16_f32 v70, v60, v61
	v_add_u32_e32 v60, 0xa0, v146
	global_store_dwordx4 v[100:101], v[88:91], off offset:256 nt
	v_cvt_pk_bf16_f32 v71, v62, v63
	v_mad_i64_i32 v[60:61], s[14:15], v60, s88, v[158:159]
	v_lshl_add_u64 v[88:89], v[80:81], 0, v[160:161]
	v_cvt_pk_bf16_f32 v44, v44, v45
	v_cvt_pk_bf16_f32 v45, v46, v47
	v_cvt_pk_bf16_f32 v46, v40, v41
	v_add_u32_e32 v40, 0xb0, v146
	global_store_dwordx4 v[88:89], v[68:71], off offset:256 nt
	v_cvt_pk_bf16_f32 v47, v42, v43
	v_mad_i64_i32 v[40:41], s[14:15], v40, s88, v[158:159]
	v_lshl_add_u64 v[68:69], v[60:61], 0, v[160:161]
	v_cvt_pk_bf16_f32 v154, v92, v93
	v_cvt_pk_bf16_f32 v155, v94, v95
	v_cvt_pk_bf16_f32 v156, v84, v85
	v_cvt_pk_bf16_f32 v157, v86, v87
	v_cvt_pk_bf16_f32 v120, v76, v77
	v_cvt_pk_bf16_f32 v121, v78, v79
	v_cvt_pk_bf16_f32 v122, v72, v73
	v_cvt_pk_bf16_f32 v123, v74, v75
	v_cvt_pk_bf16_f32 v112, v64, v65
	v_cvt_pk_bf16_f32 v113, v66, v67
	v_cvt_pk_bf16_f32 v114, v56, v57
	v_cvt_pk_bf16_f32 v115, v58, v59
	v_cvt_pk_bf16_f32 v104, v52, v53
	v_cvt_pk_bf16_f32 v105, v54, v55
	v_cvt_pk_bf16_f32 v106, v48, v49
	v_cvt_pk_bf16_f32 v107, v50, v51
	v_cvt_pk_bf16_f32 v96, v32, v33
	v_cvt_pk_bf16_f32 v97, v34, v35
	v_cvt_pk_bf16_f32 v98, v24, v25
	v_cvt_pk_bf16_f32 v99, v26, v27
	v_cvt_pk_bf16_f32 v80, v20, v21
	v_cvt_pk_bf16_f32 v81, v22, v23
	v_cvt_pk_bf16_f32 v82, v16, v17
	v_cvt_pk_bf16_f32 v83, v18, v19
	v_cvt_pk_bf16_f32 v60, v12, v13
	v_cvt_pk_bf16_f32 v61, v14, v15
	v_cvt_pk_bf16_f32 v62, v8, v9
	v_cvt_pk_bf16_f32 v63, v10, v11
	global_store_dwordx4 v[68:69], v[44:47], off offset:256 nt
	v_cvt_pk_bf16_f32 v42, v0, v1
	v_cvt_pk_bf16_f32 v43, v2, v3
	v_lshl_add_u64 v[44:45], v[40:41], 0, v[160:161]
	v_cvt_pk_bf16_f32 v40, v4, v5
	v_cvt_pk_bf16_f32 v41, v6, v7
	v_cvt_pk_bf16_f32 v36, v36, v37
	v_cvt_pk_bf16_f32 v37, v38, v39
	v_cvt_pk_bf16_f32 v38, v28, v29
	v_cvt_pk_bf16_f32 v39, v30, v31
	global_store_dwordx4 v[162:163], v[154:157], off nt
	global_store_dwordx4 v[124:125], v[120:123], off nt
	global_store_dwordx4 v[116:117], v[112:115], off nt
	global_store_dwordx4 v[108:109], v[104:107], off nt
	global_store_dwordx4 v[100:101], v[96:99], off nt
	global_store_dwordx4 v[88:89], v[80:83], off nt
	global_store_dwordx4 v[68:69], v[60:63], off nt
	global_store_dwordx4 v[44:45], v[40:43], off nt
	global_store_dwordx4 v[44:45], v[36:39], off offset:256 nt
	s_mov_b64 s[16:17], 0
